# grid barrier waiting path: this CU's L1 invalidate issued when the wait starts (no L1-cached load can be issued by the CU until the barrier exits) instead of after the release is seen
# speedup vs baseline: 1.0085x; 1.0085x over previous
; __device__ __forceinline__ unsigned xb_ld(unsigned* p)              { return __hip_atomic_load(p, __ATOMIC_RELAXED, __HIP_MEMORY_SCOPE_AGENT); }
; __device__ __forceinline__ unsigned xb_add(unsigned* p, unsigned v) { return __hip_atomic_fetch_add(p, v, __ATOMIC_RELAXED, __HIP_MEMORY_SCOPE_AGENT); }
; #define XB_SPIN(cond, bar) do { unsigned _sp = 0; while (cond) { __builtin_amdgcn_s_sleep(1); \
;     if ((++_sp & 255u) == 0u) { if (xb_ld(&(bar)[XB_TMO])) break; if (_sp > XB_SPIN_CAP) { atomicAdd(&(bar)[XB_TMO], 1u); break; } } } } while (0)
; __device__ __forceinline__ void xcd_barrier(const XcdBarrier& b) {
;     ...
;         const unsigned old = xb_add(&bar[XB_XSUB(b.x)], 1u);
;         const unsigned gen = old / nloc;
;         if (old + 1u == (gen + 1u) * nloc) {
;             __builtin_amdgcn_fence(__ATOMIC_RELEASE, "agent");
;             asm volatile("s_waitcnt vmcnt(0)" ::: "memory");
;             const unsigned og = xb_add(&bar[XB_TOP], 1u);
;             const unsigned tg = og / nx;
;             if (og + 1u == (tg + 1u) * nx) xb_add(&bar[XB_TOPGEN], 1u);
;             else XB_SPIN(xb_ld(&bar[XB_TOPGEN]) == tg, bar);
;             __builtin_amdgcn_fence(__ATOMIC_ACQUIRE, "agent");
;             xb_add(&bar[XB_XGEN(b.x)], 1u);
;             asm volatile("s_waitcnt vmcnt(0)" ::: "memory");
;         } else {
;             XB_SPIN(xb_ld(&bar[XB_XGEN(b.x)]) == gen, bar);
;             __builtin_amdgcn_fence(__ATOMIC_ACQUIRE, "agent");
;             asm volatile("s_waitcnt vmcnt(0)" ::: "memory");
.LBB0_50:
	s_or_b64 exec, exec, s[8:9]
	v_cvt_f32_u32_e32 v4, v2
	s_waitcnt vmcnt(0)
	v_readfirstlane_b32 s6, v3
	v_sub_u32_e32 v3, 0, v2
	v_rcp_iflag_f32_e32 v4, v4
	v_add_u32_e32 v5, s6, v1
	v_mul_f32_e32 v4, 0x4f7ffffe, v4
	v_cvt_u32_f32_e32 v4, v4
	v_mul_lo_u32 v1, v3, v4
	v_mul_hi_u32 v1, v4, v1
	v_add_u32_e32 v1, v4, v1
	v_mul_hi_u32 v1, v5, v1
	v_mul_lo_u32 v3, v1, v2
	v_sub_u32_e32 v3, v5, v3
	v_add_u32_e32 v4, 1, v1
	v_cmp_ge_u32_e32 vcc, v3, v2
	s_nop 1
	v_cndmask_b32_e32 v1, v1, v4, vcc
	v_sub_u32_e32 v4, v3, v2
	v_cndmask_b32_e32 v3, v3, v4, vcc
	v_add_u32_e32 v4, 1, v1
	v_cmp_ge_u32_e32 vcc, v3, v2
	v_add_u32_e32 v3, 1, v5
	s_nop 0
	v_cndmask_b32_e32 v1, v1, v4, vcc
	v_mul_lo_u32 v4, v2, v1
	v_add_u32_e32 v2, v4, v2
	v_cmp_ne_u32_e32 vcc, v3, v2
	s_and_saveexec_b64 s[6:7], vcc
	s_xor_b64 s[6:7], exec, s[6:7]
	s_cbranch_execz .LBB0_64
	buffer_inv sc1
	s_waitcnt lgkmcnt(0)
	v_mov_b32_e32 v0, 0x2000
	global_load_dword v0, v0, s[4:5] offset:1024 sc1
	s_add_u32 s12, s4, 0x2400
	s_addc_u32 s13, s5, 0
	s_waitcnt vmcnt(0)
	v_cmp_eq_u32_e32 vcc, v0, v1
	s_and_saveexec_b64 s[8:9], vcc
	s_cbranch_execz .LBB0_63
	s_add_u32 s10, s50, 0xfc0200
	s_addc_u32 s11, s51, 0
	s_mov_b32 s26, 1
	s_mov_b64 s[14:15], 0
	v_mov_b32_e32 v0, 0
	s_branch .LBB0_54

; __device__ __forceinline__ unsigned xb_ld(unsigned* p)              { return __hip_atomic_load(p, __ATOMIC_RELAXED, __HIP_MEMORY_SCOPE_AGENT); }
; #define XB_SPIN(cond, bar) do { unsigned _sp = 0; while (cond) { __builtin_amdgcn_s_sleep(1); \
;     if ((++_sp & 255u) == 0u) { if (xb_ld(&(bar)[XB_TMO])) break; if (_sp > XB_SPIN_CAP) { atomicAdd(&(bar)[XB_TMO], 1u); break; } } } } while (0)
; __device__ __forceinline__ void xcd_barrier(const XcdBarrier& b) {
;     ...
;             XB_SPIN(xb_ld(&bar[XB_XGEN(b.x)]) == gen, bar);
;             __builtin_amdgcn_fence(__ATOMIC_ACQUIRE, "agent");
;             asm volatile("s_waitcnt vmcnt(0)" ::: "memory");
.LBB0_63:
	s_or_b64 exec, exec, s[8:9]
	s_waitcnt vmcnt(0)
	s_waitcnt vmcnt(0)

; __device__ __forceinline__ unsigned xb_ld(unsigned* p)              { return __hip_atomic_load(p, __ATOMIC_RELAXED, __HIP_MEMORY_SCOPE_AGENT); }
; __device__ __forceinline__ unsigned xb_add(unsigned* p, unsigned v) { return __hip_atomic_fetch_add(p, v, __ATOMIC_RELAXED, __HIP_MEMORY_SCOPE_AGENT); }
; #define XB_SPIN(cond, bar) do { unsigned _sp = 0; while (cond) { __builtin_amdgcn_s_sleep(1); \
;     if ((++_sp & 255u) == 0u) { if (xb_ld(&(bar)[XB_TMO])) break; if (_sp > XB_SPIN_CAP) { atomicAdd(&(bar)[XB_TMO], 1u); break; } } } } while (0)
; __device__ __forceinline__ void xcd_barrier(const XcdBarrier& b) {
;     ...
;         const unsigned old = xb_add(&bar[XB_XSUB(b.x)], 1u);
;         const unsigned gen = old / nloc;
;         if (old + 1u == (gen + 1u) * nloc) {
;             __builtin_amdgcn_fence(__ATOMIC_RELEASE, "agent");
;             asm volatile("s_waitcnt vmcnt(0)" ::: "memory");
;             const unsigned og = xb_add(&bar[XB_TOP], 1u);
;             const unsigned tg = og / nx;
;             if (og + 1u == (tg + 1u) * nx) xb_add(&bar[XB_TOPGEN], 1u);
;             else XB_SPIN(xb_ld(&bar[XB_TOPGEN]) == tg, bar);
;             __builtin_amdgcn_fence(__ATOMIC_ACQUIRE, "agent");
;             xb_add(&bar[XB_XGEN(b.x)], 1u);
;             asm volatile("s_waitcnt vmcnt(0)" ::: "memory");
;         } else {
;             XB_SPIN(xb_ld(&bar[XB_XGEN(b.x)]) == gen, bar);
;             __builtin_amdgcn_fence(__ATOMIC_ACQUIRE, "agent");
;             asm volatile("s_waitcnt vmcnt(0)" ::: "memory");
.LBB0_376:
	s_or_b64 exec, exec, s[8:9]
	v_cvt_f32_u32_e32 v4, v2
	s_waitcnt vmcnt(0)
	v_readfirstlane_b32 s6, v3
	v_sub_u32_e32 v3, 0, v2
	v_rcp_iflag_f32_e32 v4, v4
	v_add_u32_e32 v5, s6, v1
	v_mul_f32_e32 v4, 0x4f7ffffe, v4
	v_cvt_u32_f32_e32 v4, v4
	v_mul_lo_u32 v1, v3, v4
	v_mul_hi_u32 v1, v4, v1
	v_add_u32_e32 v1, v4, v1
	v_mul_hi_u32 v1, v5, v1
	v_mul_lo_u32 v3, v1, v2
	v_sub_u32_e32 v3, v5, v3
	v_add_u32_e32 v4, 1, v1
	v_cmp_ge_u32_e32 vcc, v3, v2
	s_nop 1
	v_cndmask_b32_e32 v1, v1, v4, vcc
	v_sub_u32_e32 v4, v3, v2
	v_cndmask_b32_e32 v3, v3, v4, vcc
	v_add_u32_e32 v4, 1, v1
	v_cmp_ge_u32_e32 vcc, v3, v2
	v_add_u32_e32 v3, 1, v5
	s_nop 0
	v_cndmask_b32_e32 v1, v1, v4, vcc
	v_mul_lo_u32 v4, v2, v1
	v_add_u32_e32 v2, v4, v2
	v_cmp_ne_u32_e32 vcc, v3, v2
	s_and_saveexec_b64 s[6:7], vcc
	s_xor_b64 s[6:7], exec, s[6:7]
	s_cbranch_execz .LBB0_390
	buffer_inv sc1
	s_waitcnt lgkmcnt(0)
	v_mov_b32_e32 v0, 0x2000
	global_load_dword v0, v0, s[4:5] offset:1024 sc1
	s_add_u32 s12, s4, 0x2400
	s_addc_u32 s13, s5, 0
	s_waitcnt vmcnt(0)
	v_cmp_eq_u32_e32 vcc, v0, v1
	s_and_saveexec_b64 s[8:9], vcc
	s_cbranch_execz .LBB0_389
	s_add_u32 s10, s50, 0xfc0200
	s_addc_u32 s11, s51, 0
	s_mov_b32 s28, 1
	s_mov_b64 s[14:15], 0
	v_mov_b32_e32 v0, 0
	s_branch .LBB0_380

; __device__ __forceinline__ unsigned xb_ld(unsigned* p)              { return __hip_atomic_load(p, __ATOMIC_RELAXED, __HIP_MEMORY_SCOPE_AGENT); }
; __device__ __forceinline__ unsigned xb_add(unsigned* p, unsigned v) { return __hip_atomic_fetch_add(p, v, __ATOMIC_RELAXED, __HIP_MEMORY_SCOPE_AGENT); }
; #define XB_SPIN(cond, bar) do { unsigned _sp = 0; while (cond) { __builtin_amdgcn_s_sleep(1); \
;     if ((++_sp & 255u) == 0u) { if (xb_ld(&(bar)[XB_TMO])) break; if (_sp > XB_SPIN_CAP) { atomicAdd(&(bar)[XB_TMO], 1u); break; } } } } while (0)
; __device__ __forceinline__ void xcd_barrier(const XcdBarrier& b) {
;     ...
;         const unsigned old = xb_add(&bar[XB_XSUB(b.x)], 1u);
;         const unsigned gen = old / nloc;
;         if (old + 1u == (gen + 1u) * nloc) {
;             __builtin_amdgcn_fence(__ATOMIC_RELEASE, "agent");
;             asm volatile("s_waitcnt vmcnt(0)" ::: "memory");
;             const unsigned og = xb_add(&bar[XB_TOP], 1u);
;             const unsigned tg = og / nx;
;             if (og + 1u == (tg + 1u) * nx) xb_add(&bar[XB_TOPGEN], 1u);
;             else XB_SPIN(xb_ld(&bar[XB_TOPGEN]) == tg, bar);
;             __builtin_amdgcn_fence(__ATOMIC_ACQUIRE, "agent");
;             xb_add(&bar[XB_XGEN(b.x)], 1u);
;             asm volatile("s_waitcnt vmcnt(0)" ::: "memory");
;         } else {
;             XB_SPIN(xb_ld(&bar[XB_XGEN(b.x)]) == gen, bar);
;             __builtin_amdgcn_fence(__ATOMIC_ACQUIRE, "agent");
;             asm volatile("s_waitcnt vmcnt(0)" ::: "memory");
.LBB0_492:
	s_or_b64 exec, exec, s[8:9]
	v_cvt_f32_u32_e32 v4, v2
	s_waitcnt vmcnt(0)
	v_readfirstlane_b32 s6, v3
	v_sub_u32_e32 v3, 0, v2
	v_rcp_iflag_f32_e32 v4, v4
	v_add_u32_e32 v5, s6, v1
	v_mul_f32_e32 v4, 0x4f7ffffe, v4
	v_cvt_u32_f32_e32 v4, v4
	v_mul_lo_u32 v1, v3, v4
	v_mul_hi_u32 v1, v4, v1
	v_add_u32_e32 v1, v4, v1
	v_mul_hi_u32 v1, v5, v1
	v_mul_lo_u32 v3, v1, v2
	v_sub_u32_e32 v3, v5, v3
	v_add_u32_e32 v4, 1, v1
	v_cmp_ge_u32_e32 vcc, v3, v2
	s_nop 1
	v_cndmask_b32_e32 v1, v1, v4, vcc
	v_sub_u32_e32 v4, v3, v2
	v_cndmask_b32_e32 v3, v3, v4, vcc
	v_add_u32_e32 v4, 1, v1
	v_cmp_ge_u32_e32 vcc, v3, v2
	v_add_u32_e32 v3, 1, v5
	s_nop 0
	v_cndmask_b32_e32 v1, v1, v4, vcc
	v_mul_lo_u32 v4, v2, v1
	v_add_u32_e32 v2, v4, v2
	v_cmp_ne_u32_e32 vcc, v3, v2
	s_and_saveexec_b64 s[6:7], vcc
	s_xor_b64 s[6:7], exec, s[6:7]
	s_cbranch_execz .LBB0_506
	buffer_inv sc1
	s_waitcnt lgkmcnt(0)
	v_mov_b32_e32 v0, 0x2000
	global_load_dword v0, v0, s[4:5] offset:1024 sc1
	s_add_u32 s12, s4, 0x2400
	s_addc_u32 s13, s5, 0
	s_waitcnt vmcnt(0)
	v_cmp_eq_u32_e32 vcc, v0, v1
	s_and_saveexec_b64 s[8:9], vcc
	s_cbranch_execz .LBB0_505
	s_add_u32 s10, s50, 0xfc0200
	s_addc_u32 s11, s51, 0
	s_mov_b32 s30, 1
	s_mov_b64 s[14:15], 0
	v_mov_b32_e32 v0, 0
	s_branch .LBB0_496

; __device__ __forceinline__ unsigned xb_ld(unsigned* p)              { return __hip_atomic_load(p, __ATOMIC_RELAXED, __HIP_MEMORY_SCOPE_AGENT); }
; __device__ __forceinline__ unsigned xb_add(unsigned* p, unsigned v) { return __hip_atomic_fetch_add(p, v, __ATOMIC_RELAXED, __HIP_MEMORY_SCOPE_AGENT); }
; #define XB_SPIN(cond, bar) do { unsigned _sp = 0; while (cond) { __builtin_amdgcn_s_sleep(1); \
;     if ((++_sp & 255u) == 0u) { if (xb_ld(&(bar)[XB_TMO])) break; if (_sp > XB_SPIN_CAP) { atomicAdd(&(bar)[XB_TMO], 1u); break; } } } } while (0)
; __device__ __forceinline__ void xcd_barrier(const XcdBarrier& b) {
;     ...
;         const unsigned old = xb_add(&bar[XB_XSUB(b.x)], 1u);
;         const unsigned gen = old / nloc;
;         if (old + 1u == (gen + 1u) * nloc) {
;             __builtin_amdgcn_fence(__ATOMIC_RELEASE, "agent");
;             asm volatile("s_waitcnt vmcnt(0)" ::: "memory");
;             const unsigned og = xb_add(&bar[XB_TOP], 1u);
;             const unsigned tg = og / nx;
;             if (og + 1u == (tg + 1u) * nx) xb_add(&bar[XB_TOPGEN], 1u);
;             else XB_SPIN(xb_ld(&bar[XB_TOPGEN]) == tg, bar);
;             __builtin_amdgcn_fence(__ATOMIC_ACQUIRE, "agent");
;             xb_add(&bar[XB_XGEN(b.x)], 1u);
;             asm volatile("s_waitcnt vmcnt(0)" ::: "memory");
;         } else {
;             XB_SPIN(xb_ld(&bar[XB_XGEN(b.x)]) == gen, bar);
;             __builtin_amdgcn_fence(__ATOMIC_ACQUIRE, "agent");
;             asm volatile("s_waitcnt vmcnt(0)" ::: "memory");
.LBB0_586:
	s_or_b64 exec, exec, s[14:15]
	v_cvt_f32_u32_e32 v4, v2
	s_waitcnt vmcnt(0)
	v_readfirstlane_b32 s8, v3
	v_sub_u32_e32 v3, 0, v2
	v_rcp_iflag_f32_e32 v4, v4
	v_add_u32_e32 v5, s8, v1
	v_mul_f32_e32 v4, 0x4f7ffffe, v4
	v_cvt_u32_f32_e32 v4, v4
	v_mul_lo_u32 v1, v3, v4
	v_mul_hi_u32 v1, v4, v1
	v_add_u32_e32 v1, v4, v1
	v_mul_hi_u32 v1, v5, v1
	v_mul_lo_u32 v3, v1, v2
	v_sub_u32_e32 v3, v5, v3
	v_add_u32_e32 v4, 1, v1
	v_cmp_ge_u32_e32 vcc, v3, v2
	s_nop 1
	v_cndmask_b32_e32 v1, v1, v4, vcc
	v_sub_u32_e32 v4, v3, v2
	v_cndmask_b32_e32 v3, v3, v4, vcc
	v_add_u32_e32 v4, 1, v1
	v_cmp_ge_u32_e32 vcc, v3, v2
	v_add_u32_e32 v3, 1, v5
	s_nop 0
	v_cndmask_b32_e32 v1, v1, v4, vcc
	v_mul_lo_u32 v4, v2, v1
	v_add_u32_e32 v2, v4, v2
	v_cmp_ne_u32_e32 vcc, v3, v2
	s_and_saveexec_b64 s[8:9], vcc
	s_xor_b64 s[8:9], exec, s[8:9]
	s_cbranch_execz .LBB0_600
	buffer_inv sc1
	s_waitcnt lgkmcnt(0)
	v_mov_b32_e32 v0, 0x2000
	global_load_dword v0, v0, s[6:7] offset:1024 sc1
	s_add_u32 s24, s6, 0x2400
	s_addc_u32 s25, s7, 0
	s_waitcnt vmcnt(0)
	v_cmp_eq_u32_e32 vcc, v0, v1
	s_and_saveexec_b64 s[14:15], vcc
	s_cbranch_execz .LBB0_599
	s_add_u32 s16, s50, 0xfc0200
	s_addc_u32 s17, s51, 0
	s_mov_b32 s33, 1
	s_mov_b64 s[26:27], 0
	v_mov_b32_e32 v0, 0
	s_branch .LBB0_590

; __device__ __forceinline__ unsigned xb_ld(unsigned* p)              { return __hip_atomic_load(p, __ATOMIC_RELAXED, __HIP_MEMORY_SCOPE_AGENT); }
; #define XB_SPIN(cond, bar) do { unsigned _sp = 0; while (cond) { __builtin_amdgcn_s_sleep(1); \
;     if ((++_sp & 255u) == 0u) { if (xb_ld(&(bar)[XB_TMO])) break; if (_sp > XB_SPIN_CAP) { atomicAdd(&(bar)[XB_TMO], 1u); break; } } } } while (0)
; __device__ __forceinline__ void xcd_barrier(const XcdBarrier& b) {
;     ...
;             XB_SPIN(xb_ld(&bar[XB_XGEN(b.x)]) == gen, bar);
;             __builtin_amdgcn_fence(__ATOMIC_ACQUIRE, "agent");
;             asm volatile("s_waitcnt vmcnt(0)" ::: "memory");
.LBB0_599:
	s_or_b64 exec, exec, s[14:15]
	s_waitcnt vmcnt(0)
	s_waitcnt vmcnt(0)

; __device__ __forceinline__ unsigned xb_ld(unsigned* p)              { return __hip_atomic_load(p, __ATOMIC_RELAXED, __HIP_MEMORY_SCOPE_AGENT); }
; __device__ __forceinline__ unsigned xb_add(unsigned* p, unsigned v) { return __hip_atomic_fetch_add(p, v, __ATOMIC_RELAXED, __HIP_MEMORY_SCOPE_AGENT); }
; #define XB_SPIN(cond, bar) do { unsigned _sp = 0; while (cond) { __builtin_amdgcn_s_sleep(1); \
;     if ((++_sp & 255u) == 0u) { if (xb_ld(&(bar)[XB_TMO])) break; if (_sp > XB_SPIN_CAP) { atomicAdd(&(bar)[XB_TMO], 1u); break; } } } } while (0)
; __device__ __forceinline__ void xcd_barrier(const XcdBarrier& b) {
;     ...
;         const unsigned old = xb_add(&bar[XB_XSUB(b.x)], 1u);
;         const unsigned gen = old / nloc;
;         if (old + 1u == (gen + 1u) * nloc) {
;             __builtin_amdgcn_fence(__ATOMIC_RELEASE, "agent");
;             asm volatile("s_waitcnt vmcnt(0)" ::: "memory");
;             const unsigned og = xb_add(&bar[XB_TOP], 1u);
;             const unsigned tg = og / nx;
;             if (og + 1u == (tg + 1u) * nx) xb_add(&bar[XB_TOPGEN], 1u);
;             else XB_SPIN(xb_ld(&bar[XB_TOPGEN]) == tg, bar);
;             __builtin_amdgcn_fence(__ATOMIC_ACQUIRE, "agent");
;             xb_add(&bar[XB_XGEN(b.x)], 1u);
;             asm volatile("s_waitcnt vmcnt(0)" ::: "memory");
;         } else {
;             XB_SPIN(xb_ld(&bar[XB_XGEN(b.x)]) == gen, bar);
;             __builtin_amdgcn_fence(__ATOMIC_ACQUIRE, "agent");
;             asm volatile("s_waitcnt vmcnt(0)" ::: "memory");
.LBB0_662:
	s_or_b64 exec, exec, s[14:15]
	v_cvt_f32_u32_e32 v4, v2
	s_waitcnt vmcnt(0)
	v_readfirstlane_b32 s3, v3
	v_sub_u32_e32 v3, 0, v2
	v_rcp_iflag_f32_e32 v4, v4
	v_add_u32_e32 v5, s3, v1
	v_mul_f32_e32 v4, 0x4f7ffffe, v4
	v_cvt_u32_f32_e32 v4, v4
	v_mul_lo_u32 v1, v3, v4
	v_mul_hi_u32 v1, v4, v1
	v_add_u32_e32 v1, v4, v1
	v_mul_hi_u32 v1, v5, v1
	v_mul_lo_u32 v3, v1, v2
	v_sub_u32_e32 v3, v5, v3
	v_add_u32_e32 v4, 1, v1
	v_cmp_ge_u32_e32 vcc, v3, v2
	s_nop 1
	v_cndmask_b32_e32 v1, v1, v4, vcc
	v_sub_u32_e32 v4, v3, v2
	v_cndmask_b32_e32 v3, v3, v4, vcc
	v_add_u32_e32 v4, 1, v1
	v_cmp_ge_u32_e32 vcc, v3, v2
	v_add_u32_e32 v3, 1, v5
	s_nop 0
	v_cndmask_b32_e32 v1, v1, v4, vcc
	v_mul_lo_u32 v4, v2, v1
	v_add_u32_e32 v2, v4, v2
	v_cmp_ne_u32_e32 vcc, v3, v2
	s_and_saveexec_b64 s[8:9], vcc
	s_xor_b64 s[8:9], exec, s[8:9]
	s_cbranch_execz .LBB0_676
	buffer_inv sc1
	s_waitcnt lgkmcnt(0)
	v_mov_b32_e32 v0, 0x2000
	global_load_dword v0, v0, s[6:7] offset:1024 sc1
	s_add_u32 s18, s6, 0x2400
	s_addc_u32 s19, s7, 0
	s_waitcnt vmcnt(0)
	v_cmp_eq_u32_e32 vcc, v0, v1
	s_and_saveexec_b64 s[14:15], vcc
	s_cbranch_execz .LBB0_675
	s_add_u32 s16, s50, 0xfc0200
	s_addc_u32 s17, s51, 0
	s_mov_b32 s3, 1
	s_mov_b64 s[22:23], 0
	v_mov_b32_e32 v0, 0
	s_branch .LBB0_666
